# v54 with the now-dead shuffle-address VALU block of the SSD prompt unit output stage removed
# speedup vs baseline: 1.0165x; 1.0031x over previous
.LBB0_368:
	v_add_u32_e32 v218, v128, v132
	ds_read_b128 v[74:77], v218
	ds_read_b128 v[220:223], v203
	ds_read_b128 v[78:81], v218 offset:64
	ds_read_b128 v[224:227], v203 offset:64
	ds_read_b128 v[228:231], v218 offset:128
	ds_read_b128 v[232:235], v203 offset:128
	ds_read_b128 v[236:239], v218 offset:192
	s_waitcnt lgkmcnt(6)
	v_mfma_f32_16x16x32_bf16 v[74:77], v[66:69], v[74:77], 0
	s_waitcnt lgkmcnt(5)
	v_mfma_f32_16x16x32_bf16 v[220:223], v[66:69], v[220:223], 0
	ds_read_b128 v[66:69], v203 offset:192
	s_waitcnt lgkmcnt(5)
	v_mfma_f32_16x16x32_bf16 v[74:77], v[62:65], v[78:81], v[74:77]
	s_waitcnt lgkmcnt(4)
	v_mfma_f32_16x16x32_bf16 v[220:223], v[62:65], v[224:227], v[220:223]
	s_waitcnt lgkmcnt(3)
	v_mfma_f32_16x16x32_bf16 v[74:77], v[58:61], v[228:231], v[74:77]
	s_waitcnt lgkmcnt(2)
	v_mfma_f32_16x16x32_bf16 v[220:223], v[58:61], v[232:235], v[220:223]
	s_waitcnt lgkmcnt(1)
	v_mfma_f32_16x16x32_bf16 v[74:77], v[70:73], v[236:239], v[74:77]
	s_waitcnt lgkmcnt(0)
	v_mfma_f32_16x16x32_bf16 v[58:61], v[70:73], v[66:69], v[220:223]
	s_waitcnt vmcnt(9)
	s_nop 7
	ds_read_b32 v62, v166
	ds_read_u16 v68, v167
	ds_read_u16 v73, v167 offset:32
	s_waitcnt lgkmcnt(2)
	v_mul_f32_e32 v62, 0x3fb8aa3b, v62
	v_exp_f32_e32 v72, v62
	s_waitcnt lgkmcnt(1)
	v_lshlrev_b32_e32 v68, 16, v68
	v_add_u32_e32 v62, -3, v118
	v_ashrrev_i32_e32 v63, 31, v62
	v_fma_f32 v54, v74, v72, v54
	v_fmac_f32_e32 v54, v208, v68
	v_lshlrev_b32_e32 v68, 16, v217
	v_mul_f32_e32 v69, 0xbfb8aa3b, v68
	v_exp_f32_e32 v69, v69
	v_fma_f32 v50, v58, v72, v50
	v_lshlrev_b32_e32 v58, 16, v216
	v_add_f32_e32 v69, 1.0, v69
	v_rcp_f32_e32 v69, v69
	s_nop 0
	v_mul_f32_e32 v68, v69, v68
	v_mul_f32_e32 v54, v68, v54
	v_lshlrev_b64 v[68:69], 12, v[62:63]
	v_lshl_or_b32 v68, s94, 1, v68
	v_cvt_pk_bf16_f32 v74, v54, s0
	v_lshl_add_u64 v[70:71], v[98:99], 0, v[68:69]
	global_store_short v[70:71], v74, off
	s_waitcnt lgkmcnt(0)
	v_lshlrev_b32_e32 v70, 16, v73
	v_fmac_f32_e32 v50, v208, v70
	v_mul_f32_e32 v70, 0xbfb8aa3b, v58
	v_exp_f32_e32 v70, v70
	v_lshl_add_u64 v[68:69], v[116:117], 0, v[68:69]
	v_add_f32_e32 v70, 1.0, v70
	v_rcp_f32_e32 v70, v70
	s_nop 0
	v_mul_f32_e32 v58, v70, v58
	v_mul_f32_e32 v50, v58, v50
	v_mul_f32_e32 v58, v50, v50
	v_fmac_f32_e32 v58, v54, v54
	v_cvt_pk_bf16_f32 v50, v50, s0
	global_store_short v[68:69], v50, off
	s_waitcnt lgkmcnt(0)
	s_nop 1
	v_add_f32_dpp v50, v58, v58 quad_perm:[1,0,3,2] row_mask:0xf bank_mask:0xf
	s_waitcnt lgkmcnt(0)
	s_nop 1
	v_add_f32_dpp v50, v50, v50 quad_perm:[2,3,0,1] row_mask:0xf bank_mask:0xf
	s_waitcnt lgkmcnt(0)
	s_nop 1
	v_add_f32_dpp v50, v50, v50 row_half_mirror row_mask:0xf bank_mask:0xf
	s_nop 1
	v_add_f32_dpp v54, v50, v50 row_mirror row_mask:0xf bank_mask:0xf
	s_and_saveexec_b64 s[24:25], s[4:5]
	s_cbranch_execz .LBB0_370
	v_lshlrev_b64 v[62:63], 8, v[62:63]
	s_waitcnt lgkmcnt(0)
	v_mov_b32_e32 v50, v54
	v_lshl_add_u64 v[62:63], s[88:89], 0, v[62:63]
	global_store_dword v[62:63], v50, off
